# grid barrier: XCD leader publishes the XCD-local generation before its own L1 invalidate (release not serialized behind buffer_inv)
# speedup vs baseline: 1.0101x; 1.0101x over previous
.LBB0_767:
	s_or_b64 exec, exec, s[4:5]
	s_mov_b64 s[4:5], exec
	v_mbcnt_lo_u32_b32 v0, s4, 0
	v_mbcnt_hi_u32_b32 v0, s5, v0
	v_cmp_eq_u32_e32 vcc, 0, v0
	s_waitcnt vmcnt(0)
	s_and_saveexec_b64 s[6:7], vcc
	s_cbranch_execz .LBB0_769
	s_bcnt1_i32_b64 s4, s[4:5]
	v_mov_b32_e32 v0, s4
	v_readlane_b32 s4, v251, 28
	v_readlane_b32 s5, v251, 29
	s_nop 4
	global_atomic_add v1, v0, s[4:5]
.LBB0_769:
	s_or_b64 exec, exec, s[6:7]
	buffer_inv sc1
	s_waitcnt vmcnt(0)
